# grid barrier: all workgroups wait on the cross-XCD arrival counter reaching (gen+1)*nx; TOPGEN/XGEN relay hops removed (empty barrier 6.5 -> 2 us)
# baseline (speedup 1.0000x reference)
; __device__ __forceinline__ unsigned xb_ld(unsigned* p)              { return __hip_atomic_load(p, __ATOMIC_RELAXED, __HIP_MEMORY_SCOPE_AGENT); }
; __device__ __forceinline__ unsigned xb_add(unsigned* p, unsigned v) { return __hip_atomic_fetch_add(p, v, __ATOMIC_RELAXED, __HIP_MEMORY_SCOPE_AGENT); }
; #define XB_SPIN(cond, bar) do { unsigned _sp = 0; while (cond) { __builtin_amdgcn_s_sleep(1); \
;     if ((++_sp & 255u) == 0u) { if (xb_ld(&(bar)[XB_TMO])) break; if (_sp > XB_SPIN_CAP) { atomicAdd(&(bar)[XB_TMO], 1u); break; } } } } while (0)
; __device__ __forceinline__ void xcd_barrier(const XcdBarrier& b) {
;     ...
;         const unsigned old = xb_add(&bar[XB_XSUB(b.x)], 1u);
;         const unsigned gen = old / nloc;
;         if (old + 1u == (gen + 1u) * nloc) {
;             __builtin_amdgcn_fence(__ATOMIC_RELEASE, "agent");
;             asm volatile("s_waitcnt vmcnt(0)" ::: "memory");
;             const unsigned og = xb_add(&bar[XB_TOP], 1u);
;             const unsigned tg = og / nx;
;             if (og + 1u == (tg + 1u) * nx) xb_add(&bar[XB_TOPGEN], 1u);
;             else XB_SPIN(xb_ld(&bar[XB_TOPGEN]) == tg, bar);
;             __builtin_amdgcn_fence(__ATOMIC_ACQUIRE, "agent");
;             xb_add(&bar[XB_XGEN(b.x)], 1u);
;             asm volatile("s_waitcnt vmcnt(0)" ::: "memory");
;         } else {
;             XB_SPIN(xb_ld(&bar[XB_XGEN(b.x)]) == gen, bar);
.LBB0_109:
	s_or_b64 exec, exec, s[42:43]
	v_cvt_f32_u32_e32 v4, v2
	s_waitcnt vmcnt(0)
	v_readfirstlane_b32 s19, v3
	v_sub_u32_e32 v3, 0, v2
	v_rcp_iflag_f32_e32 v4, v4
	v_add_u32_e32 v5, s19, v1
	v_mul_f32_e32 v4, 0x4f7ffffe, v4
	v_cvt_u32_f32_e32 v4, v4
	v_mul_lo_u32 v1, v3, v4
	v_mul_hi_u32 v1, v4, v1
	v_add_u32_e32 v1, v4, v1
	v_mul_hi_u32 v1, v5, v1
	v_mul_lo_u32 v3, v1, v2
	v_sub_u32_e32 v3, v5, v3
	v_add_u32_e32 v4, 1, v1
	v_sub_u32_e32 v6, v3, v2
	v_cmp_ge_u32_e32 vcc, v3, v2
	s_nop 1
	v_cndmask_b32_e32 v1, v1, v4, vcc
	v_cndmask_b32_e32 v3, v3, v6, vcc
	v_add_u32_e32 v4, 1, v1
	v_cmp_ge_u32_e32 vcc, v3, v2
	v_add_u32_e32 v3, 1, v5
	s_nop 0
	v_cndmask_b32_e32 v1, v1, v4, vcc
	v_mul_lo_u32 v4, v2, v1
	v_add_u32_e32 v2, v4, v2
	v_cmp_ne_u32_e32 vcc, v3, v2
	s_and_saveexec_b64 s[20:21], vcc
	s_xor_b64 s[42:43], exec, s[20:21]
	s_cbranch_execz .LBB0_123
	v_readlane_b32 s0, v249, 35
	v_readlane_b32 s1, v249, 36
	s_waitcnt lgkmcnt(0)
	v_add_u32_e32 v6, 1, v1
	v_mul_lo_u32 v6, v6, v0
	s_nop 3
	global_load_dword v0, v193, s[0:1] sc1
	s_waitcnt vmcnt(0)
	v_cmp_lt_u32_e32 vcc, v0, v6
	s_and_saveexec_b64 s[48:49], vcc
	s_cbranch_execz .LBB0_122
	s_mov_b32 s19, 1
	s_mov_b64 s[50:51], 0
	s_branch .LBB0_113

; __device__ __forceinline__ unsigned xb_ld(unsigned* p)              { return __hip_atomic_load(p, __ATOMIC_RELAXED, __HIP_MEMORY_SCOPE_AGENT); }
; __device__ __forceinline__ unsigned xb_add(unsigned* p, unsigned v) { return __hip_atomic_fetch_add(p, v, __ATOMIC_RELAXED, __HIP_MEMORY_SCOPE_AGENT); }
; #define XB_SPIN(cond, bar) do { unsigned _sp = 0; while (cond) { __builtin_amdgcn_s_sleep(1); \
;     if ((++_sp & 255u) == 0u) { if (xb_ld(&(bar)[XB_TMO])) break; if (_sp > XB_SPIN_CAP) { atomicAdd(&(bar)[XB_TMO], 1u); break; } } } } while (0)
; __device__ __forceinline__ void xcd_barrier(const XcdBarrier& b) {
;     ...
;             else XB_SPIN(xb_ld(&bar[XB_TOPGEN]) == tg, bar);
;             __builtin_amdgcn_fence(__ATOMIC_ACQUIRE, "agent");
;             xb_add(&bar[XB_XGEN(b.x)], 1u);
;             asm volatile("s_waitcnt vmcnt(0)" ::: "memory");
;         } else {
;             XB_SPIN(xb_ld(&bar[XB_XGEN(b.x)]) == gen, bar);
.LBB0_115:
	v_readlane_b32 s0, v249, 35
	v_readlane_b32 s1, v249, 36
	s_add_i32 s19, s19, 1
	s_mov_b64 s[56:57], -1
	s_nop 2
	global_load_dword v0, v193, s[0:1] sc1
	s_waitcnt vmcnt(0)
	v_cmp_ge_u32_e32 vcc, v0, v6
	s_orn2_b64 s[54:55], vcc, exec
	s_branch .LBB0_112

; __device__ __forceinline__ unsigned xb_ld(unsigned* p)              { return __hip_atomic_load(p, __ATOMIC_RELAXED, __HIP_MEMORY_SCOPE_AGENT); }
; __device__ __forceinline__ unsigned xb_add(unsigned* p, unsigned v) { return __hip_atomic_fetch_add(p, v, __ATOMIC_RELAXED, __HIP_MEMORY_SCOPE_AGENT); }
; #define XB_SPIN(cond, bar) do { unsigned _sp = 0; while (cond) { __builtin_amdgcn_s_sleep(1); \
;     if ((++_sp & 255u) == 0u) { if (xb_ld(&(bar)[XB_TMO])) break; if (_sp > XB_SPIN_CAP) { atomicAdd(&(bar)[XB_TMO], 1u); break; } } } } while (0)
; __device__ __forceinline__ void xcd_barrier(const XcdBarrier& b) {
;     ...
;         if (old + 1u == (gen + 1u) * nloc) {
;             __builtin_amdgcn_fence(__ATOMIC_RELEASE, "agent");
;             asm volatile("s_waitcnt vmcnt(0)" ::: "memory");
;             const unsigned og = xb_add(&bar[XB_TOP], 1u);
;             const unsigned tg = og / nx;
;             if (og + 1u == (tg + 1u) * nx) xb_add(&bar[XB_TOPGEN], 1u);
;             else XB_SPIN(xb_ld(&bar[XB_TOPGEN]) == tg, bar);
.LBB0_126:
	s_or_b64 exec, exec, s[48:49]
	v_cvt_f32_u32_e32 v3, v0
	s_waitcnt vmcnt(0)
	v_readfirstlane_b32 s19, v2
	v_sub_u32_e32 v2, 0, v0
	v_readlane_b32 s0, v249, 35
	v_rcp_iflag_f32_e32 v3, v3
	v_add_u32_e32 v1, s19, v1
	v_add_u32_e32 v4, 1, v1
	v_readlane_b32 s1, v249, 36
	v_mul_f32_e32 v3, 0x4f7ffffe, v3
	v_cvt_u32_f32_e32 v3, v3
	s_mov_b64 s[48:49], 0
	v_mul_lo_u32 v2, v2, v3
	v_mul_hi_u32 v2, v3, v2
	v_add_u32_e32 v2, v3, v2
	v_mul_hi_u32 v2, v1, v2
	v_mul_lo_u32 v3, v2, v0
	v_sub_u32_e32 v1, v1, v3
	v_add_u32_e32 v5, 1, v2
	v_sub_u32_e32 v3, v1, v0
	v_cmp_ge_u32_e32 vcc, v1, v0
	s_nop 1
	v_cndmask_b32_e32 v2, v2, v5, vcc
	v_cndmask_b32_e32 v1, v1, v3, vcc
	v_add_u32_e32 v3, 1, v2
	v_cmp_ge_u32_e32 vcc, v1, v0
	s_nop 1
	v_cndmask_b32_e32 v2, v2, v3, vcc
	v_mul_lo_u32 v1, v0, v2
	v_add_u32_e32 v0, v1, v0
	v_cmp_ne_u32_e32 vcc, v4, v0
	v_mov_b32_e32 v6, v0
	v_mov_b64_e32 v[0:1], s[0:1]
	s_and_saveexec_b64 s[42:43], vcc
	s_cbranch_execz .LBB0_138
	v_readlane_b32 s0, v249, 35
	v_readlane_b32 s1, v249, 36
	s_mov_b64 s[50:51], 0
	s_nop 3
	global_load_dword v0, v193, s[0:1] sc1
	s_waitcnt vmcnt(0)
	v_cmp_lt_u32_e32 vcc, v0, v6
	s_and_saveexec_b64 s[48:49], vcc
	s_cbranch_execz .LBB0_137
	s_mov_b32 s19, 1
	s_branch .LBB0_130

; __device__ __forceinline__ unsigned xb_add(unsigned* p, unsigned v) { return __hip_atomic_fetch_add(p, v, __ATOMIC_RELAXED, __HIP_MEMORY_SCOPE_AGENT); }
; __device__ __forceinline__ void xcd_barrier(const XcdBarrier& b) {
;     ...
;             __builtin_amdgcn_fence(__ATOMIC_ACQUIRE, "agent");
;             xb_add(&bar[XB_XGEN(b.x)], 1u);
;             asm volatile("s_waitcnt vmcnt(0)" ::: "memory");
.LBB0_140:
	s_or_b64 exec, exec, s[42:43]
	s_mov_b64 s[42:43], exec
	v_mbcnt_lo_u32_b32 v0, s42, 0
	v_mbcnt_hi_u32_b32 v0, s43, v0
	v_cmp_eq_u32_e32 vcc, 0, v0
	s_waitcnt vmcnt(0)
	buffer_inv sc1
	s_and_saveexec_b64 s[48:49], vcc
	s_cbranch_execz .LBB0_142
	s_bcnt1_i32_b64 s19, s[42:43]
	v_readlane_b32 s0, v249, 33
	v_mov_b32_e32 v0, s19
	v_readlane_b32 s1, v249, 34
	s_nop 4
	s_nop 0

; __device__ __forceinline__ unsigned xb_ld(unsigned* p)              { return __hip_atomic_load(p, __ATOMIC_RELAXED, __HIP_MEMORY_SCOPE_AGENT); }
; __device__ __forceinline__ unsigned xb_add(unsigned* p, unsigned v) { return __hip_atomic_fetch_add(p, v, __ATOMIC_RELAXED, __HIP_MEMORY_SCOPE_AGENT); }
; #define XB_SPIN(cond, bar) do { unsigned _sp = 0; while (cond) { __builtin_amdgcn_s_sleep(1); \
;     if ((++_sp & 255u) == 0u) { if (xb_ld(&(bar)[XB_TMO])) break; if (_sp > XB_SPIN_CAP) { atomicAdd(&(bar)[XB_TMO], 1u); break; } } } } while (0)
; __device__ __forceinline__ void xcd_barrier(const XcdBarrier& b) {
;     ...
;         const unsigned old = xb_add(&bar[XB_XSUB(b.x)], 1u);
;         const unsigned gen = old / nloc;
;         if (old + 1u == (gen + 1u) * nloc) {
;             __builtin_amdgcn_fence(__ATOMIC_RELEASE, "agent");
;             asm volatile("s_waitcnt vmcnt(0)" ::: "memory");
;             const unsigned og = xb_add(&bar[XB_TOP], 1u);
;             const unsigned tg = og / nx;
;             if (og + 1u == (tg + 1u) * nx) xb_add(&bar[XB_TOPGEN], 1u);
;             else XB_SPIN(xb_ld(&bar[XB_TOPGEN]) == tg, bar);
;             __builtin_amdgcn_fence(__ATOMIC_ACQUIRE, "agent");
;             xb_add(&bar[XB_XGEN(b.x)], 1u);
;             asm volatile("s_waitcnt vmcnt(0)" ::: "memory");
;         } else {
;             XB_SPIN(xb_ld(&bar[XB_XGEN(b.x)]) == gen, bar);
.LBB0_279:
	s_or_b64 exec, exec, s[40:41]
	v_cvt_f32_u32_e32 v4, v2
	s_waitcnt vmcnt(0)
	v_readfirstlane_b32 s19, v3
	v_sub_u32_e32 v3, 0, v2
	v_rcp_iflag_f32_e32 v4, v4
	v_add_u32_e32 v5, s19, v1
	v_mul_f32_e32 v4, 0x4f7ffffe, v4
	v_cvt_u32_f32_e32 v4, v4
	v_mul_lo_u32 v1, v3, v4
	v_mul_hi_u32 v1, v4, v1
	v_add_u32_e32 v1, v4, v1
	v_mul_hi_u32 v1, v5, v1
	v_mul_lo_u32 v3, v1, v2
	v_sub_u32_e32 v3, v5, v3
	v_add_u32_e32 v4, 1, v1
	v_cmp_ge_u32_e32 vcc, v3, v2
	s_nop 1
	v_cndmask_b32_e32 v1, v1, v4, vcc
	v_sub_u32_e32 v4, v3, v2
	v_cndmask_b32_e32 v3, v3, v4, vcc
	v_add_u32_e32 v4, 1, v1
	v_cmp_ge_u32_e32 vcc, v3, v2
	v_add_u32_e32 v3, 1, v5
	s_nop 0
	v_cndmask_b32_e32 v1, v1, v4, vcc
	v_mul_lo_u32 v4, v2, v1
	v_add_u32_e32 v2, v4, v2
	v_cmp_ne_u32_e32 vcc, v3, v2
	s_and_saveexec_b64 s[20:21], vcc
	s_xor_b64 s[40:41], exec, s[20:21]
	s_cbranch_execz .LBB0_293
	v_readlane_b32 s0, v249, 35
	v_readlane_b32 s1, v249, 36
	s_waitcnt lgkmcnt(0)
	v_add_u32_e32 v6, 1, v1
	v_mul_lo_u32 v6, v6, v0
	s_nop 3
	global_load_dword v0, v193, s[0:1] sc1
	s_waitcnt vmcnt(0)
	v_cmp_lt_u32_e32 vcc, v0, v6
	s_and_saveexec_b64 s[42:43], vcc
	s_cbranch_execz .LBB0_292
	s_mov_b32 s19, 1
	s_mov_b64 s[48:49], 0
	s_branch .LBB0_283

; __device__ __forceinline__ unsigned xb_ld(unsigned* p)              { return __hip_atomic_load(p, __ATOMIC_RELAXED, __HIP_MEMORY_SCOPE_AGENT); }
; __device__ __forceinline__ unsigned xb_add(unsigned* p, unsigned v) { return __hip_atomic_fetch_add(p, v, __ATOMIC_RELAXED, __HIP_MEMORY_SCOPE_AGENT); }
; #define XB_SPIN(cond, bar) do { unsigned _sp = 0; while (cond) { __builtin_amdgcn_s_sleep(1); \
;     if ((++_sp & 255u) == 0u) { if (xb_ld(&(bar)[XB_TMO])) break; if (_sp > XB_SPIN_CAP) { atomicAdd(&(bar)[XB_TMO], 1u); break; } } } } while (0)
; __device__ __forceinline__ void xcd_barrier(const XcdBarrier& b) {
;     ...
;             else XB_SPIN(xb_ld(&bar[XB_TOPGEN]) == tg, bar);
;             __builtin_amdgcn_fence(__ATOMIC_ACQUIRE, "agent");
;             xb_add(&bar[XB_XGEN(b.x)], 1u);
;             asm volatile("s_waitcnt vmcnt(0)" ::: "memory");
;         } else {
;             XB_SPIN(xb_ld(&bar[XB_XGEN(b.x)]) == gen, bar);
.LBB0_285:
	v_readlane_b32 s0, v249, 35
	v_readlane_b32 s1, v249, 36
	s_add_i32 s19, s19, 1
	s_mov_b64 s[54:55], -1
	s_nop 2
	global_load_dword v0, v193, s[0:1] sc1
	s_waitcnt vmcnt(0)
	v_cmp_ge_u32_e32 vcc, v0, v6
	s_orn2_b64 s[52:53], vcc, exec
	s_branch .LBB0_282

; __device__ __forceinline__ unsigned xb_ld(unsigned* p)              { return __hip_atomic_load(p, __ATOMIC_RELAXED, __HIP_MEMORY_SCOPE_AGENT); }
; __device__ __forceinline__ unsigned xb_add(unsigned* p, unsigned v) { return __hip_atomic_fetch_add(p, v, __ATOMIC_RELAXED, __HIP_MEMORY_SCOPE_AGENT); }
; #define XB_SPIN(cond, bar) do { unsigned _sp = 0; while (cond) { __builtin_amdgcn_s_sleep(1); \
;     if ((++_sp & 255u) == 0u) { if (xb_ld(&(bar)[XB_TMO])) break; if (_sp > XB_SPIN_CAP) { atomicAdd(&(bar)[XB_TMO], 1u); break; } } } } while (0)
; __device__ __forceinline__ void xcd_barrier(const XcdBarrier& b) {
;     ...
;         if (old + 1u == (gen + 1u) * nloc) {
;             __builtin_amdgcn_fence(__ATOMIC_RELEASE, "agent");
;             asm volatile("s_waitcnt vmcnt(0)" ::: "memory");
;             const unsigned og = xb_add(&bar[XB_TOP], 1u);
;             const unsigned tg = og / nx;
;             if (og + 1u == (tg + 1u) * nx) xb_add(&bar[XB_TOPGEN], 1u);
;             else XB_SPIN(xb_ld(&bar[XB_TOPGEN]) == tg, bar);
.LBB0_296:
	s_or_b64 exec, exec, s[42:43]
	s_waitcnt vmcnt(0)
	v_readfirstlane_b32 s19, v2
	v_cvt_f32_u32_e32 v2, v0
	v_sub_u32_e32 v3, 0, v0
	v_add_u32_e32 v1, s19, v1
	v_readlane_b32 s0, v249, 35
	v_rcp_iflag_f32_e32 v2, v2
	v_readlane_b32 s1, v249, 36
	s_mov_b64 s[42:43], 0
	v_mul_f32_e32 v2, 0x4f7ffffe, v2
	v_cvt_u32_f32_e32 v2, v2
	v_mul_lo_u32 v3, v3, v2
	v_mul_hi_u32 v3, v2, v3
	v_add_u32_e32 v2, v2, v3
	v_mul_hi_u32 v2, v1, v2
	v_mul_lo_u32 v3, v2, v0
	v_sub_u32_e32 v3, v1, v3
	v_cmp_ge_u32_e32 vcc, v3, v0
	v_add_u32_e32 v4, 1, v2
	v_add_u32_e32 v1, 1, v1
	v_cndmask_b32_e32 v2, v2, v4, vcc
	v_sub_u32_e32 v4, v3, v0
	v_cndmask_b32_e32 v3, v3, v4, vcc
	v_cmp_ge_u32_e32 vcc, v3, v0
	v_add_u32_e32 v3, 1, v2
	s_nop 0
	v_cndmask_b32_e32 v2, v2, v3, vcc
	v_mul_lo_u32 v3, v0, v2
	v_add_u32_e32 v0, v3, v0
	v_cmp_ne_u32_e32 vcc, v1, v0
	v_mov_b32_e32 v6, v0
	v_mov_b64_e32 v[0:1], s[0:1]
	s_and_saveexec_b64 s[40:41], vcc
	s_cbranch_execz .LBB0_308
	v_readlane_b32 s0, v249, 35
	v_readlane_b32 s1, v249, 36
	s_mov_b64 s[48:49], 0
	s_nop 3
	global_load_dword v0, v193, s[0:1] sc1
	s_waitcnt vmcnt(0)
	v_cmp_lt_u32_e32 vcc, v0, v6
	s_and_saveexec_b64 s[42:43], vcc
	s_cbranch_execz .LBB0_307
	s_mov_b32 s19, 1
	s_branch .LBB0_300

; __device__ __forceinline__ unsigned xb_add(unsigned* p, unsigned v) { return __hip_atomic_fetch_add(p, v, __ATOMIC_RELAXED, __HIP_MEMORY_SCOPE_AGENT); }
; __device__ __forceinline__ void xcd_barrier(const XcdBarrier& b) {
;     ...
;             __builtin_amdgcn_fence(__ATOMIC_ACQUIRE, "agent");
;             xb_add(&bar[XB_XGEN(b.x)], 1u);
;             asm volatile("s_waitcnt vmcnt(0)" ::: "memory");
.LBB0_310:
	s_or_b64 exec, exec, s[40:41]
	s_mov_b64 s[40:41], exec
	v_mbcnt_lo_u32_b32 v0, s40, 0
	v_mbcnt_hi_u32_b32 v0, s41, v0
	v_cmp_eq_u32_e32 vcc, 0, v0
	s_waitcnt vmcnt(0)
	buffer_inv sc1
	s_and_saveexec_b64 s[42:43], vcc
	s_cbranch_execz .LBB0_312
	s_bcnt1_i32_b64 s19, s[40:41]
	v_readlane_b32 s0, v249, 33
	v_mov_b32_e32 v0, s19
	v_readlane_b32 s1, v249, 34
	s_nop 4
	s_nop 0

; __device__ __forceinline__ unsigned xb_ld(unsigned* p)              { return __hip_atomic_load(p, __ATOMIC_RELAXED, __HIP_MEMORY_SCOPE_AGENT); }
; __device__ __forceinline__ unsigned xb_add(unsigned* p, unsigned v) { return __hip_atomic_fetch_add(p, v, __ATOMIC_RELAXED, __HIP_MEMORY_SCOPE_AGENT); }
; #define XB_SPIN(cond, bar) do { unsigned _sp = 0; while (cond) { __builtin_amdgcn_s_sleep(1); \
;     if ((++_sp & 255u) == 0u) { if (xb_ld(&(bar)[XB_TMO])) break; if (_sp > XB_SPIN_CAP) { atomicAdd(&(bar)[XB_TMO], 1u); break; } } } } while (0)
; __device__ __forceinline__ void xcd_barrier(const XcdBarrier& b) {
;     ...
;         const unsigned old = xb_add(&bar[XB_XSUB(b.x)], 1u);
;         const unsigned gen = old / nloc;
;         if (old + 1u == (gen + 1u) * nloc) {
;             __builtin_amdgcn_fence(__ATOMIC_RELEASE, "agent");
;             asm volatile("s_waitcnt vmcnt(0)" ::: "memory");
;             const unsigned og = xb_add(&bar[XB_TOP], 1u);
;             const unsigned tg = og / nx;
;             if (og + 1u == (tg + 1u) * nx) xb_add(&bar[XB_TOPGEN], 1u);
;             else XB_SPIN(xb_ld(&bar[XB_TOPGEN]) == tg, bar);
;             __builtin_amdgcn_fence(__ATOMIC_ACQUIRE, "agent");
;             xb_add(&bar[XB_XGEN(b.x)], 1u);
;             asm volatile("s_waitcnt vmcnt(0)" ::: "memory");
;         } else {
;             XB_SPIN(xb_ld(&bar[XB_XGEN(b.x)]) == gen, bar);
.LBB0_590:
	s_or_b64 exec, exec, s[40:41]
	v_cvt_f32_u32_e32 v4, v2
	s_waitcnt vmcnt(0)
	v_readfirstlane_b32 s19, v3
	v_sub_u32_e32 v3, 0, v2
	v_rcp_iflag_f32_e32 v4, v4
	v_add_u32_e32 v5, s19, v1
	v_mul_f32_e32 v4, 0x4f7ffffe, v4
	v_cvt_u32_f32_e32 v4, v4
	v_mul_lo_u32 v1, v3, v4
	v_mul_hi_u32 v1, v4, v1
	v_add_u32_e32 v1, v4, v1
	v_mul_hi_u32 v1, v5, v1
	v_mul_lo_u32 v3, v1, v2
	v_sub_u32_e32 v3, v5, v3
	v_add_u32_e32 v4, 1, v1
	v_cmp_ge_u32_e32 vcc, v3, v2
	s_nop 1
	v_cndmask_b32_e32 v1, v1, v4, vcc
	v_sub_u32_e32 v4, v3, v2
	v_cndmask_b32_e32 v3, v3, v4, vcc
	v_add_u32_e32 v4, 1, v1
	v_cmp_ge_u32_e32 vcc, v3, v2
	v_add_u32_e32 v3, 1, v5
	s_nop 0
	v_cndmask_b32_e32 v1, v1, v4, vcc
	v_mul_lo_u32 v4, v2, v1
	v_add_u32_e32 v2, v4, v2
	v_cmp_ne_u32_e32 vcc, v3, v2
	s_and_saveexec_b64 s[20:21], vcc
	s_xor_b64 s[40:41], exec, s[20:21]
	s_cbranch_execz .LBB0_604
	v_readlane_b32 s0, v249, 35
	v_readlane_b32 s1, v249, 36
	s_waitcnt lgkmcnt(0)
	v_add_u32_e32 v6, 1, v1
	v_mul_lo_u32 v6, v6, v0
	s_nop 3
	global_load_dword v0, v193, s[0:1] sc1
	s_waitcnt vmcnt(0)
	v_cmp_lt_u32_e32 vcc, v0, v6
	s_and_saveexec_b64 s[42:43], vcc
	s_cbranch_execz .LBB0_603
	s_mov_b32 s19, 1
	s_mov_b64 s[44:45], 0
	s_branch .LBB0_594

; __device__ __forceinline__ unsigned xb_ld(unsigned* p)              { return __hip_atomic_load(p, __ATOMIC_RELAXED, __HIP_MEMORY_SCOPE_AGENT); }
; __device__ __forceinline__ unsigned xb_add(unsigned* p, unsigned v) { return __hip_atomic_fetch_add(p, v, __ATOMIC_RELAXED, __HIP_MEMORY_SCOPE_AGENT); }
; #define XB_SPIN(cond, bar) do { unsigned _sp = 0; while (cond) { __builtin_amdgcn_s_sleep(1); \
;     if ((++_sp & 255u) == 0u) { if (xb_ld(&(bar)[XB_TMO])) break; if (_sp > XB_SPIN_CAP) { atomicAdd(&(bar)[XB_TMO], 1u); break; } } } } while (0)
; __device__ __forceinline__ void xcd_barrier(const XcdBarrier& b) {
;     ...
;             else XB_SPIN(xb_ld(&bar[XB_TOPGEN]) == tg, bar);
;             __builtin_amdgcn_fence(__ATOMIC_ACQUIRE, "agent");
;             xb_add(&bar[XB_XGEN(b.x)], 1u);
;             asm volatile("s_waitcnt vmcnt(0)" ::: "memory");
;         } else {
;             XB_SPIN(xb_ld(&bar[XB_XGEN(b.x)]) == gen, bar);
.LBB0_596:
	v_readlane_b32 s0, v249, 35
	v_readlane_b32 s1, v249, 36
	s_add_i32 s19, s19, 1
	s_mov_b64 s[50:51], -1
	s_nop 2
	global_load_dword v0, v193, s[0:1] sc1
	s_waitcnt vmcnt(0)
	v_cmp_ge_u32_e32 vcc, v0, v6
	s_orn2_b64 s[48:49], vcc, exec
	s_branch .LBB0_593

; __device__ __forceinline__ unsigned xb_ld(unsigned* p)              { return __hip_atomic_load(p, __ATOMIC_RELAXED, __HIP_MEMORY_SCOPE_AGENT); }
; __device__ __forceinline__ unsigned xb_add(unsigned* p, unsigned v) { return __hip_atomic_fetch_add(p, v, __ATOMIC_RELAXED, __HIP_MEMORY_SCOPE_AGENT); }
; #define XB_SPIN(cond, bar) do { unsigned _sp = 0; while (cond) { __builtin_amdgcn_s_sleep(1); \
;     if ((++_sp & 255u) == 0u) { if (xb_ld(&(bar)[XB_TMO])) break; if (_sp > XB_SPIN_CAP) { atomicAdd(&(bar)[XB_TMO], 1u); break; } } } } while (0)
; __device__ __forceinline__ void xcd_barrier(const XcdBarrier& b) {
;     ...
;         if (old + 1u == (gen + 1u) * nloc) {
;             __builtin_amdgcn_fence(__ATOMIC_RELEASE, "agent");
;             asm volatile("s_waitcnt vmcnt(0)" ::: "memory");
;             const unsigned og = xb_add(&bar[XB_TOP], 1u);
;             const unsigned tg = og / nx;
;             if (og + 1u == (tg + 1u) * nx) xb_add(&bar[XB_TOPGEN], 1u);
;             else XB_SPIN(xb_ld(&bar[XB_TOPGEN]) == tg, bar);
.LBB0_607:
	s_or_b64 exec, exec, s[42:43]
	s_waitcnt vmcnt(0)
	v_readfirstlane_b32 s19, v2
	v_cvt_f32_u32_e32 v2, v0
	v_sub_u32_e32 v3, 0, v0
	v_add_u32_e32 v1, s19, v1
	v_readlane_b32 s0, v249, 35
	v_rcp_iflag_f32_e32 v2, v2
	v_readlane_b32 s1, v249, 36
	s_mov_b64 s[42:43], 0
	v_mul_f32_e32 v2, 0x4f7ffffe, v2
	v_cvt_u32_f32_e32 v2, v2
	v_mul_lo_u32 v3, v3, v2
	v_mul_hi_u32 v3, v2, v3
	v_add_u32_e32 v2, v2, v3
	v_mul_hi_u32 v2, v1, v2
	v_mul_lo_u32 v3, v2, v0
	v_sub_u32_e32 v3, v1, v3
	v_cmp_ge_u32_e32 vcc, v3, v0
	v_add_u32_e32 v4, 1, v2
	v_add_u32_e32 v1, 1, v1
	v_cndmask_b32_e32 v2, v2, v4, vcc
	v_sub_u32_e32 v4, v3, v0
	v_cndmask_b32_e32 v3, v3, v4, vcc
	v_cmp_ge_u32_e32 vcc, v3, v0
	v_add_u32_e32 v3, 1, v2
	s_nop 0
	v_cndmask_b32_e32 v2, v2, v3, vcc
	v_mul_lo_u32 v3, v0, v2
	v_add_u32_e32 v0, v3, v0
	v_cmp_ne_u32_e32 vcc, v1, v0
	v_mov_b32_e32 v6, v0
	v_mov_b64_e32 v[0:1], s[0:1]
	s_and_saveexec_b64 s[40:41], vcc
	s_cbranch_execz .LBB0_619
	v_readlane_b32 s0, v249, 35
	v_readlane_b32 s1, v249, 36
	s_mov_b64 s[44:45], 0
	s_nop 3
	global_load_dword v0, v193, s[0:1] sc1
	s_waitcnt vmcnt(0)
	v_cmp_lt_u32_e32 vcc, v0, v6
	s_and_saveexec_b64 s[42:43], vcc
	s_cbranch_execz .LBB0_618
	s_mov_b32 s19, 1
	s_branch .LBB0_611

; __device__ __forceinline__ unsigned xb_ld(unsigned* p)              { return __hip_atomic_load(p, __ATOMIC_RELAXED, __HIP_MEMORY_SCOPE_AGENT); }
; __device__ __forceinline__ unsigned xb_add(unsigned* p, unsigned v) { return __hip_atomic_fetch_add(p, v, __ATOMIC_RELAXED, __HIP_MEMORY_SCOPE_AGENT); }
; #define XB_SPIN(cond, bar) do { unsigned _sp = 0; while (cond) { __builtin_amdgcn_s_sleep(1); \
;     if ((++_sp & 255u) == 0u) { if (xb_ld(&(bar)[XB_TMO])) break; if (_sp > XB_SPIN_CAP) { atomicAdd(&(bar)[XB_TMO], 1u); break; } } } } while (0)
; __device__ __forceinline__ void xcd_barrier(const XcdBarrier& b) {
;     ...
;         const unsigned old = xb_add(&bar[XB_XSUB(b.x)], 1u);
;         const unsigned gen = old / nloc;
;         if (old + 1u == (gen + 1u) * nloc) {
;             __builtin_amdgcn_fence(__ATOMIC_RELEASE, "agent");
;             asm volatile("s_waitcnt vmcnt(0)" ::: "memory");
;             const unsigned og = xb_add(&bar[XB_TOP], 1u);
;             const unsigned tg = og / nx;
;             if (og + 1u == (tg + 1u) * nx) xb_add(&bar[XB_TOPGEN], 1u);
;             else XB_SPIN(xb_ld(&bar[XB_TOPGEN]) == tg, bar);
;             __builtin_amdgcn_fence(__ATOMIC_ACQUIRE, "agent");
;             xb_add(&bar[XB_XGEN(b.x)], 1u);
;             asm volatile("s_waitcnt vmcnt(0)" ::: "memory");
;         } else {
;             XB_SPIN(xb_ld(&bar[XB_XGEN(b.x)]) == gen, bar);
.LBB0_716:
	s_or_b64 exec, exec, s[42:43]
	v_cvt_f32_u32_e32 v4, v2
	s_waitcnt vmcnt(0)
	v_readfirstlane_b32 s19, v3
	v_sub_u32_e32 v3, 0, v2
	v_rcp_iflag_f32_e32 v4, v4
	v_add_u32_e32 v5, s19, v1
	v_mul_f32_e32 v4, 0x4f7ffffe, v4
	v_cvt_u32_f32_e32 v4, v4
	v_mul_lo_u32 v1, v3, v4
	v_mul_hi_u32 v1, v4, v1
	v_add_u32_e32 v1, v4, v1
	v_mul_hi_u32 v1, v5, v1
	v_mul_lo_u32 v3, v1, v2
	v_sub_u32_e32 v3, v5, v3
	v_add_u32_e32 v4, 1, v1
	v_cmp_ge_u32_e32 vcc, v3, v2
	s_nop 1
	v_cndmask_b32_e32 v1, v1, v4, vcc
	v_sub_u32_e32 v4, v3, v2
	v_cndmask_b32_e32 v3, v3, v4, vcc
	v_add_u32_e32 v4, 1, v1
	v_cmp_ge_u32_e32 vcc, v3, v2
	v_add_u32_e32 v3, 1, v5
	s_nop 0
	v_cndmask_b32_e32 v1, v1, v4, vcc
	v_mul_lo_u32 v4, v2, v1
	v_add_u32_e32 v2, v4, v2
	v_cmp_ne_u32_e32 vcc, v3, v2
	s_and_saveexec_b64 s[20:21], vcc
	s_xor_b64 s[42:43], exec, s[20:21]
	s_cbranch_execz .LBB0_730
	v_readlane_b32 s0, v249, 35
	v_readlane_b32 s1, v249, 36
	s_waitcnt lgkmcnt(0)
	v_add_u32_e32 v6, 1, v1
	v_mul_lo_u32 v6, v6, v0
	s_nop 3
	global_load_dword v0, v193, s[0:1] sc1
	s_waitcnt vmcnt(0)
	v_cmp_lt_u32_e32 vcc, v0, v6
	s_and_saveexec_b64 s[44:45], vcc
	s_cbranch_execz .LBB0_729
	s_mov_b32 s19, 1
	s_mov_b64 s[46:47], 0
	s_branch .LBB0_720

; __device__ __forceinline__ unsigned xb_ld(unsigned* p)              { return __hip_atomic_load(p, __ATOMIC_RELAXED, __HIP_MEMORY_SCOPE_AGENT); }
; __device__ __forceinline__ unsigned xb_add(unsigned* p, unsigned v) { return __hip_atomic_fetch_add(p, v, __ATOMIC_RELAXED, __HIP_MEMORY_SCOPE_AGENT); }
; #define XB_SPIN(cond, bar) do { unsigned _sp = 0; while (cond) { __builtin_amdgcn_s_sleep(1); \
;     if ((++_sp & 255u) == 0u) { if (xb_ld(&(bar)[XB_TMO])) break; if (_sp > XB_SPIN_CAP) { atomicAdd(&(bar)[XB_TMO], 1u); break; } } } } while (0)
; __device__ __forceinline__ void xcd_barrier(const XcdBarrier& b) {
;     ...
;             else XB_SPIN(xb_ld(&bar[XB_TOPGEN]) == tg, bar);
;             __builtin_amdgcn_fence(__ATOMIC_ACQUIRE, "agent");
;             xb_add(&bar[XB_XGEN(b.x)], 1u);
;             asm volatile("s_waitcnt vmcnt(0)" ::: "memory");
;         } else {
;             XB_SPIN(xb_ld(&bar[XB_XGEN(b.x)]) == gen, bar);
.LBB0_722:
	v_readlane_b32 s0, v249, 35
	v_readlane_b32 s1, v249, 36
	s_add_i32 s19, s19, 1
	s_mov_b64 s[52:53], -1
	s_nop 2
	global_load_dword v0, v193, s[0:1] sc1
	s_waitcnt vmcnt(0)
	v_cmp_ge_u32_e32 vcc, v0, v6
	s_orn2_b64 s[50:51], vcc, exec
	s_branch .LBB0_719

; __device__ __forceinline__ unsigned xb_ld(unsigned* p)              { return __hip_atomic_load(p, __ATOMIC_RELAXED, __HIP_MEMORY_SCOPE_AGENT); }
; __device__ __forceinline__ unsigned xb_add(unsigned* p, unsigned v) { return __hip_atomic_fetch_add(p, v, __ATOMIC_RELAXED, __HIP_MEMORY_SCOPE_AGENT); }
; #define XB_SPIN(cond, bar) do { unsigned _sp = 0; while (cond) { __builtin_amdgcn_s_sleep(1); \
;     if ((++_sp & 255u) == 0u) { if (xb_ld(&(bar)[XB_TMO])) break; if (_sp > XB_SPIN_CAP) { atomicAdd(&(bar)[XB_TMO], 1u); break; } } } } while (0)
; __device__ __forceinline__ void xcd_barrier(const XcdBarrier& b) {
;     ...
;         if (old + 1u == (gen + 1u) * nloc) {
;             __builtin_amdgcn_fence(__ATOMIC_RELEASE, "agent");
;             asm volatile("s_waitcnt vmcnt(0)" ::: "memory");
;             const unsigned og = xb_add(&bar[XB_TOP], 1u);
;             const unsigned tg = og / nx;
;             if (og + 1u == (tg + 1u) * nx) xb_add(&bar[XB_TOPGEN], 1u);
;             else XB_SPIN(xb_ld(&bar[XB_TOPGEN]) == tg, bar);
.LBB0_733:
	s_or_b64 exec, exec, s[44:45]
	s_waitcnt vmcnt(0)
	v_readfirstlane_b32 s19, v2
	v_cvt_f32_u32_e32 v2, v0
	v_sub_u32_e32 v3, 0, v0
	v_add_u32_e32 v1, s19, v1
	v_readlane_b32 s0, v249, 35
	v_rcp_iflag_f32_e32 v2, v2
	v_readlane_b32 s1, v249, 36
	s_mov_b64 s[44:45], 0
	v_mul_f32_e32 v2, 0x4f7ffffe, v2
	v_cvt_u32_f32_e32 v2, v2
	v_mul_lo_u32 v3, v3, v2
	v_mul_hi_u32 v3, v2, v3
	v_add_u32_e32 v2, v2, v3
	v_mul_hi_u32 v2, v1, v2
	v_mul_lo_u32 v3, v2, v0
	v_sub_u32_e32 v3, v1, v3
	v_cmp_ge_u32_e32 vcc, v3, v0
	v_add_u32_e32 v4, 1, v2
	v_add_u32_e32 v1, 1, v1
	v_cndmask_b32_e32 v2, v2, v4, vcc
	v_sub_u32_e32 v4, v3, v0
	v_cndmask_b32_e32 v3, v3, v4, vcc
	v_cmp_ge_u32_e32 vcc, v3, v0
	v_add_u32_e32 v3, 1, v2
	s_nop 0
	v_cndmask_b32_e32 v2, v2, v3, vcc
	v_mul_lo_u32 v3, v0, v2
	v_add_u32_e32 v0, v3, v0
	v_cmp_ne_u32_e32 vcc, v1, v0
	v_mov_b32_e32 v6, v0
	v_mov_b64_e32 v[0:1], s[0:1]
	s_and_saveexec_b64 s[42:43], vcc
	s_cbranch_execz .LBB0_745
	v_readlane_b32 s0, v249, 35
	v_readlane_b32 s1, v249, 36
	s_mov_b64 s[46:47], 0
	s_nop 3
	global_load_dword v0, v193, s[0:1] sc1
	s_waitcnt vmcnt(0)
	v_cmp_lt_u32_e32 vcc, v0, v6
	s_and_saveexec_b64 s[44:45], vcc
	s_cbranch_execz .LBB0_744
	s_mov_b32 s19, 1
	s_branch .LBB0_737

; __device__ __forceinline__ unsigned xb_add(unsigned* p, unsigned v) { return __hip_atomic_fetch_add(p, v, __ATOMIC_RELAXED, __HIP_MEMORY_SCOPE_AGENT); }
; __device__ __forceinline__ void xcd_barrier(const XcdBarrier& b) {
;     ...
;             __builtin_amdgcn_fence(__ATOMIC_ACQUIRE, "agent");
;             xb_add(&bar[XB_XGEN(b.x)], 1u);
;             asm volatile("s_waitcnt vmcnt(0)" ::: "memory");
.LBB0_747:
	s_or_b64 exec, exec, s[42:43]
	s_mov_b64 s[42:43], exec
	v_mbcnt_lo_u32_b32 v0, s42, 0
	v_mbcnt_hi_u32_b32 v0, s43, v0
	v_cmp_eq_u32_e32 vcc, 0, v0
	s_waitcnt vmcnt(0)
	buffer_inv sc1
	s_and_saveexec_b64 s[44:45], vcc
	s_cbranch_execz .LBB0_749
	s_bcnt1_i32_b64 s19, s[42:43]
	v_readlane_b32 s0, v249, 33
	v_mov_b32_e32 v0, s19
	v_readlane_b32 s1, v249, 34
	s_nop 4
	s_nop 0

; __device__ __forceinline__ unsigned xb_add(unsigned* p, unsigned v) { return __hip_atomic_fetch_add(p, v, __ATOMIC_RELAXED, __HIP_MEMORY_SCOPE_AGENT); }
; __device__ __forceinline__ void xcd_barrier(const XcdBarrier& b) {
;     ...
;             __builtin_amdgcn_fence(__ATOMIC_ACQUIRE, "agent");
;             xb_add(&bar[XB_XGEN(b.x)], 1u);
;             asm volatile("s_waitcnt vmcnt(0)" ::: "memory");
.LBB0_1026:
	s_bcnt1_i32_b64 s19, s[40:41]
	v_readlane_b32 s0, v249, 33
	v_mov_b32_e32 v0, s19
	v_readlane_b32 s1, v249, 34
	s_nop 4
	s_nop 0
	s_getpc_b64 s[98:99]
